# EpiGU blocks 2-8 re-emitted: -log2e multiply and +1.0 add in packed f32 form (44 instead of 52 VALU per 8 outputs), same per-element operations
# speedup vs baseline: 1.0164x; 1.0027x over previous
;     __device__ __forceinline__ void operator()(const f32x4 (&acc)[2][2][4][2], const Unit& u, int wr, int wc, int fr, int fq) const {
;         const int row0 = u.pm * BM + wr * 64 + fr;
; #pragma unroll
;         for (int ai = 0; ai < 2; ++ai)
; #pragma unroll
;             for (int m = 0; m < 4; ++m) {
;                 const int row = row0 + ai * HALF + m * 16;
;                 float rs;
;                 if (rsc) rs = rsc[row - rbase];
;                 else {
;                     const f32x4* pp = (const f32x4*)(part + (size_t)row * 16);
;                     const f32x4 p0 = pp[0], p1 = pp[1], p2 = pp[2], p3 = pp[3];
;                     const float ssq = ((p0[0] + p0[1]) + (p0[2] + p0[3])) + ((p1[0] + p1[1]) + (p1[2] + p1[3])) + ((p2[0] + p2[1]) + (p2[2] + p2[3])) + ((p3[0] + p3[1]) + (p3[2] + p3[3]));
;                     rs = __builtin_amdgcn_rsqf(ssq * (1.0f / 1024.0f) + 1e-6f);
;                 }
.LBB0_743:
	v_mov_b32_e32 v184, 0xbfb8aa3b
	v_mov_b32_e32 v186, 1.0
	s_mov_b32 s100, 0x16000
	s_mov_b32 s101, 0
	s_mov_b32 s98, 0x6e000
	s_mov_b32 s99, 0
	v_lshl_add_u32 v148, s26, 8, v1
	s_mov_b64 s[26:27], -1
	s_and_b64 vcc, exec, s[36:37]
	v_ashrrev_i32_e32 v149, 31, v148
	s_cbranch_vccz .LBB0_745
	v_lshlrev_b64 v[156:157], 6, v[148:149]
	v_lshl_add_u64 v[168:169], s[8:9], 0, v[156:157]
	global_load_dwordx4 v[156:159], v[168:169], off
	global_load_dwordx4 v[160:163], v[168:169], off offset:16
	global_load_dwordx4 v[164:167], v[168:169], off offset:32
	s_nop 0
	global_load_dwordx4 v[168:171], v[168:169], off offset:48
	s_mov_b64 s[26:27], 0
	s_waitcnt vmcnt(0)
	v_mov_b32_e32 v172, v157
	v_mov_b32_e32 v173, v158
	v_mov_b32_e32 v157, v159
	v_mov_b32_e32 v158, v161
	v_mov_b32_e32 v159, v162
	v_mov_b32_e32 v161, v163
	v_pk_add_f32 v[156:157], v[172:173], v[156:157]
	v_pk_add_f32 v[158:159], v[158:159], v[160:161]
	v_pk_add_f32 v[156:157], v[156:157], v[156:157] op_sel:[0,1] op_sel_hi:[1,0]
	v_pk_add_f32 v[158:159], v[158:159], v[158:159] op_sel:[0,1] op_sel_hi:[1,0]
	v_add_f32_e32 v162, v164, v165
	v_add_f32_e32 v164, v166, v167
	v_mov_b32_e32 v163, v170
	v_mov_b32_e32 v165, v171
	v_mov_b32_e32 v157, v168
	v_mov_b32_e32 v159, v169
	v_pk_add_f32 v[156:157], v[156:157], v[158:159]
	v_pk_add_f32 v[158:159], v[162:163], v[164:165]
	s_nop 0
	v_pk_add_f32 v[156:157], v[156:157], v[158:159]
	s_nop 0
	v_add_f32_e32 v150, v156, v157
	v_fmamk_f32 v150, v150, 0x3a800000, v155
	v_rsq_f32_e32 v150, v150

; __device__ __forceinline__ unsigned cvt_pk_bf16(float lo, float hi) { f32x2 v = {lo, hi}; return __builtin_bit_cast(unsigned, __builtin_convertvector(v, nbf16x2e)); }
;     __device__ __forceinline__ void operator()(const f32x4 (&acc)[2][2][4][2], const Unit& u, int wr, int wc, int fr, int fq) const {
;     ...
;                 const int row = row0 + ai * HALF + m * 16;
;                 float rs;
;                 if (rsc) rs = rsc[row - rbase];
;                 else {
;                     const f32x4* pp = (const f32x4*)(part + (size_t)row * 16);
;                     const f32x4 p0 = pp[0], p1 = pp[1], p2 = pp[2], p3 = pp[3];
;                     const float ssq = ((p0[0] + p0[1]) + (p0[2] + p0[3])) + ((p1[0] + p1[1]) + (p1[2] + p1[3])) + ((p2[0] + p2[1]) + (p2[2] + p2[3])) + ((p3[0] + p3[1]) + (p3[2] + p3[3]));
;                     rs = __builtin_amdgcn_rsqf(ssq * (1.0f / 1024.0f) + 1e-6f);
;                 }
;                 float v[8];
; #pragma unroll
;                 for (int n = 0; n < 2; ++n)
; #pragma unroll
;                     for (int i = 0; i < 4; ++i) { const float g = acc[ai][0][m][n][i] * rs, up = acc[ai][1][m][n][i] * rs; v[4 * n + i] = g * __builtin_amdgcn_rcpf(1.0f + __expf(-g)) * up; }
;                 u32x4 w; w.x = cvt_pk_bf16(v[0], v[1]); w.y = cvt_pk_bf16(v[2], v[3]); w.z = cvt_pk_bf16(v[4], v[5]); w.w = cvt_pk_bf16(v[6], v[7]);
;                 *(u32x4*)(O + (size_t)row * 2816 + u.pn * HALF + wc * 32 + 8 * fq) = w;
.LBB0_751:
	s_waitcnt lgkmcnt(0)
	v_pk_mul_f32 v[110:111], v[110:111], v[116:117] op_sel_hi:[1,0]
	v_pk_mul_f32 v[112:113], v[112:113], v[116:117] op_sel_hi:[1,0]
	v_pk_mul_f32 v[106:107], v[106:107], v[116:117] op_sel_hi:[1,0]
	v_pk_mul_f32 v[108:109], v[108:109], v[116:117] op_sel_hi:[1,0]
	v_pk_mul_f32 v[176:177], v[110:111], v[184:185] op_sel_hi:[1,0]
	v_pk_mul_f32 v[178:179], v[112:113], v[184:185] op_sel_hi:[1,0]
	v_pk_mul_f32 v[180:181], v[106:107], v[184:185] op_sel_hi:[1,0]
	v_pk_mul_f32 v[182:183], v[108:109], v[184:185] op_sel_hi:[1,0]
	v_exp_f32_e32 v176, v176
	v_exp_f32_e32 v177, v177
	v_exp_f32_e32 v178, v178
	v_exp_f32_e32 v179, v179
	v_exp_f32_e32 v180, v180
	v_exp_f32_e32 v181, v181
	v_exp_f32_e32 v182, v182
	v_exp_f32_e32 v183, v183
	v_pk_add_f32 v[176:177], v[176:177], v[186:187] op_sel_hi:[1,0]
	v_pk_add_f32 v[178:179], v[178:179], v[186:187] op_sel_hi:[1,0]
	v_pk_add_f32 v[180:181], v[180:181], v[186:187] op_sel_hi:[1,0]
	v_pk_add_f32 v[182:183], v[182:183], v[186:187] op_sel_hi:[1,0]
	v_rcp_f32_e32 v176, v176
	v_rcp_f32_e32 v177, v177
	v_rcp_f32_e32 v178, v178
	v_rcp_f32_e32 v179, v179
	v_rcp_f32_e32 v180, v180
	v_rcp_f32_e32 v181, v181
	v_rcp_f32_e32 v182, v182
	v_rcp_f32_e32 v183, v183
	v_pk_mul_f32 v[102:103], v[102:103], v[116:117] op_sel_hi:[1,0]
	v_pk_mul_f32 v[104:105], v[104:105], v[116:117] op_sel_hi:[1,0]
	v_pk_mul_f32 v[98:99], v[98:99], v[116:117] op_sel_hi:[1,0]
	v_pk_mul_f32 v[100:101], v[100:101], v[116:117] op_sel_hi:[1,0]
	v_pk_mul_f32 v[110:111], v[110:111], v[176:177]
	v_pk_mul_f32 v[112:113], v[112:113], v[178:179]
	v_pk_mul_f32 v[106:107], v[106:107], v[180:181]
	v_pk_mul_f32 v[108:109], v[108:109], v[182:183]
	v_pk_mul_f32 v[102:103], v[102:103], v[110:111]
	v_pk_mul_f32 v[104:105], v[104:105], v[112:113]
	v_pk_mul_f32 v[106:107], v[98:99], v[106:107]
	v_pk_mul_f32 v[108:109], v[100:101], v[108:109]
	v_cvt_pk_bf16_f32 v98, v102, v103
	v_cvt_pk_bf16_f32 v99, v104, v105
	v_cvt_pk_bf16_f32 v100, v106, v107
	v_cvt_pk_bf16_f32 v101, v108, v109
	s_and_b64 vcc, exec, s[36:37]
	v_lshl_add_u64 v[236:237], v[236:237], 0, s[100:101]
	global_store_dwordx4 v[236:237], v[98:101], off
	s_mov_b64 s[26:27], -1
	s_nop 0
	v_or_b32_e32 v98, 32, v148
	v_ashrrev_i32_e32 v99, 31, v98
	s_cbranch_vccz .LBB0_753
	v_lshlrev_b64 v[100:101], 6, v[98:99]
	v_lshl_add_u64 v[112:113], s[8:9], 0, v[100:101]
	global_load_dwordx4 v[100:103], v[112:113], off
	global_load_dwordx4 v[104:107], v[112:113], off offset:16
	global_load_dwordx4 v[108:111], v[112:113], off offset:32
	s_nop 0
	global_load_dwordx4 v[112:115], v[112:113], off offset:48
	s_mov_b64 s[26:27], 0
	s_waitcnt vmcnt(0)
	v_mov_b32_e32 v116, v101
	v_mov_b32_e32 v117, v102
	v_mov_b32_e32 v101, v103
	v_mov_b32_e32 v102, v105
	v_mov_b32_e32 v103, v106
	v_mov_b32_e32 v105, v107
	v_pk_add_f32 v[100:101], v[116:117], v[100:101]
	v_pk_add_f32 v[102:103], v[102:103], v[104:105]
	v_pk_add_f32 v[100:101], v[100:101], v[100:101] op_sel:[0,1] op_sel_hi:[1,0]
	v_pk_add_f32 v[102:103], v[102:103], v[102:103] op_sel:[0,1] op_sel_hi:[1,0]
	v_add_f32_e32 v106, v108, v109
	v_add_f32_e32 v108, v110, v111
	v_mov_b32_e32 v107, v114
	v_mov_b32_e32 v109, v115
	v_mov_b32_e32 v101, v112
	v_mov_b32_e32 v103, v113
	v_pk_add_f32 v[100:101], v[100:101], v[102:103]
	v_pk_add_f32 v[102:103], v[106:107], v[108:109]
	s_nop 0
	v_pk_add_f32 v[100:101], v[100:101], v[102:103]
	s_nop 0
	v_add_f32_e32 v100, v100, v101
	v_fmamk_f32 v100, v100, 0x3a800000, v155
	v_rsq_f32_e32 v100, v100

; __device__ __forceinline__ unsigned cvt_pk_bf16(float lo, float hi) { f32x2 v = {lo, hi}; return __builtin_bit_cast(unsigned, __builtin_convertvector(v, nbf16x2e)); }
;     __device__ __forceinline__ void operator()(const f32x4 (&acc)[2][2][4][2], const Unit& u, int wr, int wc, int fr, int fq) const {
;     ...
;                 const int row = row0 + ai * HALF + m * 16;
;                 float rs;
;                 if (rsc) rs = rsc[row - rbase];
;                 else {
;                     const f32x4* pp = (const f32x4*)(part + (size_t)row * 16);
;                     const f32x4 p0 = pp[0], p1 = pp[1], p2 = pp[2], p3 = pp[3];
;                     const float ssq = ((p0[0] + p0[1]) + (p0[2] + p0[3])) + ((p1[0] + p1[1]) + (p1[2] + p1[3])) + ((p2[0] + p2[1]) + (p2[2] + p2[3])) + ((p3[0] + p3[1]) + (p3[2] + p3[3]));
;                     rs = __builtin_amdgcn_rsqf(ssq * (1.0f / 1024.0f) + 1e-6f);
;                 }
;                 float v[8];
; #pragma unroll
;                 for (int n = 0; n < 2; ++n)
; #pragma unroll
;                     for (int i = 0; i < 4; ++i) { const float g = acc[ai][0][m][n][i] * rs, up = acc[ai][1][m][n][i] * rs; v[4 * n + i] = g * __builtin_amdgcn_rcpf(1.0f + __expf(-g)) * up; }
;                 u32x4 w; w.x = cvt_pk_bf16(v[0], v[1]); w.y = cvt_pk_bf16(v[2], v[3]); w.z = cvt_pk_bf16(v[4], v[5]); w.w = cvt_pk_bf16(v[6], v[7]);
;                 *(u32x4*)(O + (size_t)row * 2816 + u.pn * HALF + wc * 32 + 8 * fq) = w;
.LBB0_755:
	s_waitcnt lgkmcnt(0)
	v_pk_mul_f32 v[94:95], v[94:95], v[100:101] op_sel_hi:[1,0]
	v_pk_mul_f32 v[96:97], v[96:97], v[100:101] op_sel_hi:[1,0]
	v_pk_mul_f32 v[90:91], v[90:91], v[100:101] op_sel_hi:[1,0]
	v_pk_mul_f32 v[92:93], v[92:93], v[100:101] op_sel_hi:[1,0]
	v_pk_mul_f32 v[176:177], v[94:95], v[184:185] op_sel_hi:[1,0]
	v_pk_mul_f32 v[178:179], v[96:97], v[184:185] op_sel_hi:[1,0]
	v_pk_mul_f32 v[180:181], v[90:91], v[184:185] op_sel_hi:[1,0]
	v_pk_mul_f32 v[182:183], v[92:93], v[184:185] op_sel_hi:[1,0]
	v_exp_f32_e32 v176, v176
	v_exp_f32_e32 v177, v177
	v_exp_f32_e32 v178, v178
	v_exp_f32_e32 v179, v179
	v_exp_f32_e32 v180, v180
	v_exp_f32_e32 v181, v181
	v_exp_f32_e32 v182, v182
	v_exp_f32_e32 v183, v183
	v_pk_add_f32 v[176:177], v[176:177], v[186:187] op_sel_hi:[1,0]
	v_pk_add_f32 v[178:179], v[178:179], v[186:187] op_sel_hi:[1,0]
	v_pk_add_f32 v[180:181], v[180:181], v[186:187] op_sel_hi:[1,0]
	v_pk_add_f32 v[182:183], v[182:183], v[186:187] op_sel_hi:[1,0]
	v_rcp_f32_e32 v176, v176
	v_rcp_f32_e32 v177, v177
	v_rcp_f32_e32 v178, v178
	v_rcp_f32_e32 v179, v179
	v_rcp_f32_e32 v180, v180
	v_rcp_f32_e32 v181, v181
	v_rcp_f32_e32 v182, v182
	v_rcp_f32_e32 v183, v183
	v_pk_mul_f32 v[86:87], v[86:87], v[100:101] op_sel_hi:[1,0]
	v_pk_mul_f32 v[88:89], v[88:89], v[100:101] op_sel_hi:[1,0]
	v_pk_mul_f32 v[82:83], v[82:83], v[100:101] op_sel_hi:[1,0]
	v_pk_mul_f32 v[84:85], v[84:85], v[100:101] op_sel_hi:[1,0]
	v_pk_mul_f32 v[94:95], v[94:95], v[176:177]
	v_pk_mul_f32 v[96:97], v[96:97], v[178:179]
	v_pk_mul_f32 v[90:91], v[90:91], v[180:181]
	v_pk_mul_f32 v[92:93], v[92:93], v[182:183]
	v_pk_mul_f32 v[86:87], v[86:87], v[94:95]
	v_pk_mul_f32 v[88:89], v[88:89], v[96:97]
	v_pk_mul_f32 v[90:91], v[82:83], v[90:91]
	v_pk_mul_f32 v[92:93], v[84:85], v[92:93]
	v_cvt_pk_bf16_f32 v82, v86, v87
	v_cvt_pk_bf16_f32 v83, v88, v89
	v_cvt_pk_bf16_f32 v84, v90, v91
	v_cvt_pk_bf16_f32 v85, v92, v93
	s_and_b64 vcc, exec, s[36:37]
	v_lshl_add_u64 v[236:237], v[236:237], 0, s[100:101]
	global_store_dwordx4 v[236:237], v[82:85], off
	s_mov_b64 s[26:27], -1
	s_nop 0
	v_or_b32_e32 v82, 48, v148
	v_ashrrev_i32_e32 v83, 31, v82
	s_cbranch_vccz .LBB0_757
	v_lshlrev_b64 v[84:85], 6, v[82:83]
	v_lshl_add_u64 v[96:97], s[8:9], 0, v[84:85]
	global_load_dwordx4 v[84:87], v[96:97], off
	global_load_dwordx4 v[88:91], v[96:97], off offset:16
	global_load_dwordx4 v[92:95], v[96:97], off offset:32
	s_nop 0
	global_load_dwordx4 v[96:99], v[96:97], off offset:48
	s_mov_b64 s[26:27], 0
	s_waitcnt vmcnt(0)
	v_mov_b32_e32 v100, v85
	v_mov_b32_e32 v101, v86
	v_mov_b32_e32 v85, v87
	v_mov_b32_e32 v86, v89
	v_mov_b32_e32 v87, v90
	v_mov_b32_e32 v89, v91
	v_pk_add_f32 v[84:85], v[100:101], v[84:85]
	v_pk_add_f32 v[86:87], v[86:87], v[88:89]
	v_pk_add_f32 v[84:85], v[84:85], v[84:85] op_sel:[0,1] op_sel_hi:[1,0]
	v_pk_add_f32 v[86:87], v[86:87], v[86:87] op_sel:[0,1] op_sel_hi:[1,0]
	v_add_f32_e32 v90, v92, v93
	v_add_f32_e32 v92, v94, v95
	v_mov_b32_e32 v91, v98
	v_mov_b32_e32 v93, v99
	v_mov_b32_e32 v85, v96
	v_mov_b32_e32 v87, v97
	v_pk_add_f32 v[84:85], v[84:85], v[86:87]
	v_pk_add_f32 v[86:87], v[90:91], v[92:93]
	s_nop 0
	v_pk_add_f32 v[84:85], v[84:85], v[86:87]
	s_nop 0
	v_add_f32_e32 v84, v84, v85
	v_fmamk_f32 v84, v84, 0x3a800000, v155
	v_rsq_f32_e32 v84, v84

; __device__ __forceinline__ unsigned cvt_pk_bf16(float lo, float hi) { f32x2 v = {lo, hi}; return __builtin_bit_cast(unsigned, __builtin_convertvector(v, nbf16x2e)); }
;     __device__ __forceinline__ void operator()(const f32x4 (&acc)[2][2][4][2], const Unit& u, int wr, int wc, int fr, int fq) const {
;     ...
;                 const int row = row0 + ai * HALF + m * 16;
;                 float rs;
;                 if (rsc) rs = rsc[row - rbase];
;                 else {
;                     const f32x4* pp = (const f32x4*)(part + (size_t)row * 16);
;                     const f32x4 p0 = pp[0], p1 = pp[1], p2 = pp[2], p3 = pp[3];
;                     const float ssq = ((p0[0] + p0[1]) + (p0[2] + p0[3])) + ((p1[0] + p1[1]) + (p1[2] + p1[3])) + ((p2[0] + p2[1]) + (p2[2] + p2[3])) + ((p3[0] + p3[1]) + (p3[2] + p3[3]));
;                     rs = __builtin_amdgcn_rsqf(ssq * (1.0f / 1024.0f) + 1e-6f);
;                 }
;                 float v[8];
; #pragma unroll
;                 for (int n = 0; n < 2; ++n)
; #pragma unroll
;                     for (int i = 0; i < 4; ++i) { const float g = acc[ai][0][m][n][i] * rs, up = acc[ai][1][m][n][i] * rs; v[4 * n + i] = g * __builtin_amdgcn_rcpf(1.0f + __expf(-g)) * up; }
;                 u32x4 w; w.x = cvt_pk_bf16(v[0], v[1]); w.y = cvt_pk_bf16(v[2], v[3]); w.z = cvt_pk_bf16(v[4], v[5]); w.w = cvt_pk_bf16(v[6], v[7]);
;                 *(u32x4*)(O + (size_t)row * 2816 + u.pn * HALF + wc * 32 + 8 * fq) = w;
.LBB0_759:
	s_waitcnt lgkmcnt(0)
	v_pk_mul_f32 v[78:79], v[78:79], v[84:85] op_sel_hi:[1,0]
	v_pk_mul_f32 v[80:81], v[80:81], v[84:85] op_sel_hi:[1,0]
	v_pk_mul_f32 v[74:75], v[74:75], v[84:85] op_sel_hi:[1,0]
	v_pk_mul_f32 v[76:77], v[76:77], v[84:85] op_sel_hi:[1,0]
	v_pk_mul_f32 v[176:177], v[78:79], v[184:185] op_sel_hi:[1,0]
	v_pk_mul_f32 v[178:179], v[80:81], v[184:185] op_sel_hi:[1,0]
	v_pk_mul_f32 v[180:181], v[74:75], v[184:185] op_sel_hi:[1,0]
	v_pk_mul_f32 v[182:183], v[76:77], v[184:185] op_sel_hi:[1,0]
	v_exp_f32_e32 v176, v176
	v_exp_f32_e32 v177, v177
	v_exp_f32_e32 v178, v178
	v_exp_f32_e32 v179, v179
	v_exp_f32_e32 v180, v180
	v_exp_f32_e32 v181, v181
	v_exp_f32_e32 v182, v182
	v_exp_f32_e32 v183, v183
	v_pk_add_f32 v[176:177], v[176:177], v[186:187] op_sel_hi:[1,0]
	v_pk_add_f32 v[178:179], v[178:179], v[186:187] op_sel_hi:[1,0]
	v_pk_add_f32 v[180:181], v[180:181], v[186:187] op_sel_hi:[1,0]
	v_pk_add_f32 v[182:183], v[182:183], v[186:187] op_sel_hi:[1,0]
	v_rcp_f32_e32 v176, v176
	v_rcp_f32_e32 v177, v177
	v_rcp_f32_e32 v178, v178
	v_rcp_f32_e32 v179, v179
	v_rcp_f32_e32 v180, v180
	v_rcp_f32_e32 v181, v181
	v_rcp_f32_e32 v182, v182
	v_rcp_f32_e32 v183, v183
	v_pk_mul_f32 v[70:71], v[70:71], v[84:85] op_sel_hi:[1,0]
	v_pk_mul_f32 v[72:73], v[72:73], v[84:85] op_sel_hi:[1,0]
	v_pk_mul_f32 v[66:67], v[66:67], v[84:85] op_sel_hi:[1,0]
	v_pk_mul_f32 v[68:69], v[68:69], v[84:85] op_sel_hi:[1,0]
	v_pk_mul_f32 v[78:79], v[78:79], v[176:177]
	v_pk_mul_f32 v[80:81], v[80:81], v[178:179]
	v_pk_mul_f32 v[74:75], v[74:75], v[180:181]
	v_pk_mul_f32 v[76:77], v[76:77], v[182:183]
	v_pk_mul_f32 v[70:71], v[70:71], v[78:79]
	v_pk_mul_f32 v[72:73], v[72:73], v[80:81]
	v_pk_mul_f32 v[74:75], v[66:67], v[74:75]
	v_pk_mul_f32 v[76:77], v[68:69], v[76:77]
	v_cvt_pk_bf16_f32 v66, v70, v71
	v_cvt_pk_bf16_f32 v67, v72, v73
	v_cvt_pk_bf16_f32 v68, v74, v75
	v_cvt_pk_bf16_f32 v69, v76, v77
	s_and_b64 vcc, exec, s[36:37]
	v_lshl_add_u64 v[236:237], v[236:237], 0, s[100:101]
	global_store_dwordx4 v[236:237], v[66:69], off
	s_mov_b64 s[26:27], -1
	s_nop 0
	v_add_u32_e32 v66, 0x80, v148
	v_ashrrev_i32_e32 v67, 31, v66
	s_cbranch_vccz .LBB0_761
	v_lshlrev_b64 v[68:69], 6, v[66:67]
	v_lshl_add_u64 v[80:81], s[8:9], 0, v[68:69]
	global_load_dwordx4 v[68:71], v[80:81], off
	global_load_dwordx4 v[72:75], v[80:81], off offset:16
	global_load_dwordx4 v[76:79], v[80:81], off offset:32
	s_nop 0
	global_load_dwordx4 v[80:83], v[80:81], off offset:48
	s_mov_b64 s[26:27], 0
	s_waitcnt vmcnt(0)
	v_mov_b32_e32 v84, v69
	v_mov_b32_e32 v85, v70
	v_mov_b32_e32 v69, v71
	v_mov_b32_e32 v70, v73
	v_mov_b32_e32 v71, v74
	v_mov_b32_e32 v73, v75
	v_pk_add_f32 v[68:69], v[84:85], v[68:69]
	v_pk_add_f32 v[70:71], v[70:71], v[72:73]
	v_pk_add_f32 v[68:69], v[68:69], v[68:69] op_sel:[0,1] op_sel_hi:[1,0]
	v_pk_add_f32 v[70:71], v[70:71], v[70:71] op_sel:[0,1] op_sel_hi:[1,0]
	v_add_f32_e32 v74, v76, v77
	v_add_f32_e32 v76, v78, v79
	v_mov_b32_e32 v75, v82
	v_mov_b32_e32 v77, v83
	v_mov_b32_e32 v69, v80
	v_mov_b32_e32 v71, v81
	v_pk_add_f32 v[68:69], v[68:69], v[70:71]
	v_pk_add_f32 v[70:71], v[74:75], v[76:77]
	s_nop 0
	v_pk_add_f32 v[68:69], v[68:69], v[70:71]
	s_nop 0
	v_add_f32_e32 v68, v68, v69
	v_fmamk_f32 v68, v68, 0x3a800000, v155
	v_rsq_f32_e32 v68, v68

; __device__ __forceinline__ unsigned cvt_pk_bf16(float lo, float hi) { f32x2 v = {lo, hi}; return __builtin_bit_cast(unsigned, __builtin_convertvector(v, nbf16x2e)); }
;     __device__ __forceinline__ void operator()(const f32x4 (&acc)[2][2][4][2], const Unit& u, int wr, int wc, int fr, int fq) const {
;     ...
;                 const int row = row0 + ai * HALF + m * 16;
;                 float rs;
;                 if (rsc) rs = rsc[row - rbase];
;                 else {
;                     const f32x4* pp = (const f32x4*)(part + (size_t)row * 16);
;                     const f32x4 p0 = pp[0], p1 = pp[1], p2 = pp[2], p3 = pp[3];
;                     const float ssq = ((p0[0] + p0[1]) + (p0[2] + p0[3])) + ((p1[0] + p1[1]) + (p1[2] + p1[3])) + ((p2[0] + p2[1]) + (p2[2] + p2[3])) + ((p3[0] + p3[1]) + (p3[2] + p3[3]));
;                     rs = __builtin_amdgcn_rsqf(ssq * (1.0f / 1024.0f) + 1e-6f);
;                 }
;                 float v[8];
; #pragma unroll
;                 for (int n = 0; n < 2; ++n)
; #pragma unroll
;                     for (int i = 0; i < 4; ++i) { const float g = acc[ai][0][m][n][i] * rs, up = acc[ai][1][m][n][i] * rs; v[4 * n + i] = g * __builtin_amdgcn_rcpf(1.0f + __expf(-g)) * up; }
;                 u32x4 w; w.x = cvt_pk_bf16(v[0], v[1]); w.y = cvt_pk_bf16(v[2], v[3]); w.z = cvt_pk_bf16(v[4], v[5]); w.w = cvt_pk_bf16(v[6], v[7]);
;                 *(u32x4*)(O + (size_t)row * 2816 + u.pn * HALF + wc * 32 + 8 * fq) = w;
.LBB0_763:
	s_waitcnt lgkmcnt(0)
	v_pk_mul_f32 v[62:63], v[62:63], v[68:69] op_sel_hi:[1,0]
	v_pk_mul_f32 v[64:65], v[64:65], v[68:69] op_sel_hi:[1,0]
	v_pk_mul_f32 v[58:59], v[58:59], v[68:69] op_sel_hi:[1,0]
	v_pk_mul_f32 v[60:61], v[60:61], v[68:69] op_sel_hi:[1,0]
	v_pk_mul_f32 v[176:177], v[62:63], v[184:185] op_sel_hi:[1,0]
	v_pk_mul_f32 v[178:179], v[64:65], v[184:185] op_sel_hi:[1,0]
	v_pk_mul_f32 v[180:181], v[58:59], v[184:185] op_sel_hi:[1,0]
	v_pk_mul_f32 v[182:183], v[60:61], v[184:185] op_sel_hi:[1,0]
	v_exp_f32_e32 v176, v176
	v_exp_f32_e32 v177, v177
	v_exp_f32_e32 v178, v178
	v_exp_f32_e32 v179, v179
	v_exp_f32_e32 v180, v180
	v_exp_f32_e32 v181, v181
	v_exp_f32_e32 v182, v182
	v_exp_f32_e32 v183, v183
	v_pk_add_f32 v[176:177], v[176:177], v[186:187] op_sel_hi:[1,0]
	v_pk_add_f32 v[178:179], v[178:179], v[186:187] op_sel_hi:[1,0]
	v_pk_add_f32 v[180:181], v[180:181], v[186:187] op_sel_hi:[1,0]
	v_pk_add_f32 v[182:183], v[182:183], v[186:187] op_sel_hi:[1,0]
	v_rcp_f32_e32 v176, v176
	v_rcp_f32_e32 v177, v177
	v_rcp_f32_e32 v178, v178
	v_rcp_f32_e32 v179, v179
	v_rcp_f32_e32 v180, v180
	v_rcp_f32_e32 v181, v181
	v_rcp_f32_e32 v182, v182
	v_rcp_f32_e32 v183, v183
	v_pk_mul_f32 v[54:55], v[54:55], v[68:69] op_sel_hi:[1,0]
	v_pk_mul_f32 v[56:57], v[56:57], v[68:69] op_sel_hi:[1,0]
	v_pk_mul_f32 v[50:51], v[50:51], v[68:69] op_sel_hi:[1,0]
	v_pk_mul_f32 v[52:53], v[52:53], v[68:69] op_sel_hi:[1,0]
	v_pk_mul_f32 v[62:63], v[62:63], v[176:177]
	v_pk_mul_f32 v[64:65], v[64:65], v[178:179]
	v_pk_mul_f32 v[58:59], v[58:59], v[180:181]
	v_pk_mul_f32 v[60:61], v[60:61], v[182:183]
	v_pk_mul_f32 v[54:55], v[54:55], v[62:63]
	v_pk_mul_f32 v[56:57], v[56:57], v[64:65]
	v_pk_mul_f32 v[58:59], v[50:51], v[58:59]
	v_pk_mul_f32 v[60:61], v[52:53], v[60:61]
	v_cvt_pk_bf16_f32 v50, v54, v55
	v_cvt_pk_bf16_f32 v51, v56, v57
	v_cvt_pk_bf16_f32 v52, v58, v59
	v_cvt_pk_bf16_f32 v53, v60, v61
	s_and_b64 vcc, exec, s[36:37]
	v_lshl_add_u64 v[236:237], v[236:237], 0, s[98:99]
	global_store_dwordx4 v[236:237], v[50:53], off
	s_mov_b64 s[26:27], -1
	s_nop 0
	v_add_u32_e32 v50, 0x90, v148
	v_ashrrev_i32_e32 v51, 31, v50
	s_cbranch_vccz .LBB0_765
	v_lshlrev_b64 v[52:53], 6, v[50:51]
	v_lshl_add_u64 v[64:65], s[8:9], 0, v[52:53]
	global_load_dwordx4 v[52:55], v[64:65], off
	global_load_dwordx4 v[56:59], v[64:65], off offset:16
	global_load_dwordx4 v[60:63], v[64:65], off offset:32
	s_nop 0
	global_load_dwordx4 v[64:67], v[64:65], off offset:48
	s_mov_b64 s[26:27], 0
	s_waitcnt vmcnt(0)
	v_mov_b32_e32 v68, v53
	v_mov_b32_e32 v69, v54
	v_mov_b32_e32 v53, v55
	v_mov_b32_e32 v54, v57
	v_mov_b32_e32 v55, v58
	v_mov_b32_e32 v57, v59
	v_pk_add_f32 v[52:53], v[68:69], v[52:53]
	v_pk_add_f32 v[54:55], v[54:55], v[56:57]
	v_pk_add_f32 v[52:53], v[52:53], v[52:53] op_sel:[0,1] op_sel_hi:[1,0]
	v_pk_add_f32 v[54:55], v[54:55], v[54:55] op_sel:[0,1] op_sel_hi:[1,0]
	v_add_f32_e32 v58, v60, v61
	v_add_f32_e32 v60, v62, v63
	v_mov_b32_e32 v59, v66
	v_mov_b32_e32 v61, v67
	v_mov_b32_e32 v53, v64
	v_mov_b32_e32 v55, v65
	v_pk_add_f32 v[52:53], v[52:53], v[54:55]
	v_pk_add_f32 v[54:55], v[58:59], v[60:61]
	s_nop 0
	v_pk_add_f32 v[52:53], v[52:53], v[54:55]
	s_nop 0
	v_add_f32_e32 v52, v52, v53
	v_fmamk_f32 v52, v52, 0x3a800000, v155
	v_rsq_f32_e32 v52, v52

; __device__ __forceinline__ unsigned cvt_pk_bf16(float lo, float hi) { f32x2 v = {lo, hi}; return __builtin_bit_cast(unsigned, __builtin_convertvector(v, nbf16x2e)); }
;     __device__ __forceinline__ void operator()(const f32x4 (&acc)[2][2][4][2], const Unit& u, int wr, int wc, int fr, int fq) const {
;     ...
;                 const int row = row0 + ai * HALF + m * 16;
;                 float rs;
;                 if (rsc) rs = rsc[row - rbase];
;                 else {
;                     const f32x4* pp = (const f32x4*)(part + (size_t)row * 16);
;                     const f32x4 p0 = pp[0], p1 = pp[1], p2 = pp[2], p3 = pp[3];
;                     const float ssq = ((p0[0] + p0[1]) + (p0[2] + p0[3])) + ((p1[0] + p1[1]) + (p1[2] + p1[3])) + ((p2[0] + p2[1]) + (p2[2] + p2[3])) + ((p3[0] + p3[1]) + (p3[2] + p3[3]));
;                     rs = __builtin_amdgcn_rsqf(ssq * (1.0f / 1024.0f) + 1e-6f);
;                 }
;                 float v[8];
; #pragma unroll
;                 for (int n = 0; n < 2; ++n)
; #pragma unroll
;                     for (int i = 0; i < 4; ++i) { const float g = acc[ai][0][m][n][i] * rs, up = acc[ai][1][m][n][i] * rs; v[4 * n + i] = g * __builtin_amdgcn_rcpf(1.0f + __expf(-g)) * up; }
;                 u32x4 w; w.x = cvt_pk_bf16(v[0], v[1]); w.y = cvt_pk_bf16(v[2], v[3]); w.z = cvt_pk_bf16(v[4], v[5]); w.w = cvt_pk_bf16(v[6], v[7]);
;                 *(u32x4*)(O + (size_t)row * 2816 + u.pn * HALF + wc * 32 + 8 * fq) = w;
.LBB0_767:
	s_waitcnt lgkmcnt(0)
	v_pk_mul_f32 v[46:47], v[46:47], v[52:53] op_sel_hi:[1,0]
	v_pk_mul_f32 v[48:49], v[48:49], v[52:53] op_sel_hi:[1,0]
	v_pk_mul_f32 v[42:43], v[42:43], v[52:53] op_sel_hi:[1,0]
	v_pk_mul_f32 v[44:45], v[44:45], v[52:53] op_sel_hi:[1,0]
	v_pk_mul_f32 v[176:177], v[46:47], v[184:185] op_sel_hi:[1,0]
	v_pk_mul_f32 v[178:179], v[48:49], v[184:185] op_sel_hi:[1,0]
	v_pk_mul_f32 v[180:181], v[42:43], v[184:185] op_sel_hi:[1,0]
	v_pk_mul_f32 v[182:183], v[44:45], v[184:185] op_sel_hi:[1,0]
	v_exp_f32_e32 v176, v176
	v_exp_f32_e32 v177, v177
	v_exp_f32_e32 v178, v178
	v_exp_f32_e32 v179, v179
	v_exp_f32_e32 v180, v180
	v_exp_f32_e32 v181, v181
	v_exp_f32_e32 v182, v182
	v_exp_f32_e32 v183, v183
	v_pk_add_f32 v[176:177], v[176:177], v[186:187] op_sel_hi:[1,0]
	v_pk_add_f32 v[178:179], v[178:179], v[186:187] op_sel_hi:[1,0]
	v_pk_add_f32 v[180:181], v[180:181], v[186:187] op_sel_hi:[1,0]
	v_pk_add_f32 v[182:183], v[182:183], v[186:187] op_sel_hi:[1,0]
	v_rcp_f32_e32 v176, v176
	v_rcp_f32_e32 v177, v177
	v_rcp_f32_e32 v178, v178
	v_rcp_f32_e32 v179, v179
	v_rcp_f32_e32 v180, v180
	v_rcp_f32_e32 v181, v181
	v_rcp_f32_e32 v182, v182
	v_rcp_f32_e32 v183, v183
	v_pk_mul_f32 v[38:39], v[38:39], v[52:53] op_sel_hi:[1,0]
	v_pk_mul_f32 v[40:41], v[40:41], v[52:53] op_sel_hi:[1,0]
	v_pk_mul_f32 v[34:35], v[34:35], v[52:53] op_sel_hi:[1,0]
	v_pk_mul_f32 v[36:37], v[36:37], v[52:53] op_sel_hi:[1,0]
	v_pk_mul_f32 v[46:47], v[46:47], v[176:177]
	v_pk_mul_f32 v[48:49], v[48:49], v[178:179]
	v_pk_mul_f32 v[42:43], v[42:43], v[180:181]
	v_pk_mul_f32 v[44:45], v[44:45], v[182:183]
	v_pk_mul_f32 v[38:39], v[38:39], v[46:47]
	v_pk_mul_f32 v[40:41], v[40:41], v[48:49]
	v_pk_mul_f32 v[42:43], v[34:35], v[42:43]
	v_pk_mul_f32 v[44:45], v[36:37], v[44:45]
	v_cvt_pk_bf16_f32 v34, v38, v39
	v_cvt_pk_bf16_f32 v35, v40, v41
	v_cvt_pk_bf16_f32 v36, v42, v43
	v_cvt_pk_bf16_f32 v37, v44, v45
	s_and_b64 vcc, exec, s[36:37]
	v_lshl_add_u64 v[236:237], v[236:237], 0, s[100:101]
	global_store_dwordx4 v[236:237], v[34:37], off
	s_mov_b64 s[26:27], -1
	s_nop 0
	v_add_u32_e32 v34, 0xa0, v148
	v_ashrrev_i32_e32 v35, 31, v34
	s_cbranch_vccz .LBB0_769
	v_lshlrev_b64 v[36:37], 6, v[34:35]
	v_lshl_add_u64 v[48:49], s[8:9], 0, v[36:37]
	global_load_dwordx4 v[36:39], v[48:49], off
	global_load_dwordx4 v[40:43], v[48:49], off offset:16
	global_load_dwordx4 v[44:47], v[48:49], off offset:32
	s_nop 0
	global_load_dwordx4 v[48:51], v[48:49], off offset:48
	s_mov_b64 s[26:27], 0
	s_waitcnt vmcnt(0)
	v_mov_b32_e32 v52, v37
	v_mov_b32_e32 v53, v38
	v_mov_b32_e32 v37, v39
	v_mov_b32_e32 v38, v41
	v_mov_b32_e32 v39, v42
	v_mov_b32_e32 v41, v43
	v_pk_add_f32 v[36:37], v[52:53], v[36:37]
	v_pk_add_f32 v[38:39], v[38:39], v[40:41]
	v_pk_add_f32 v[36:37], v[36:37], v[36:37] op_sel:[0,1] op_sel_hi:[1,0]
	v_pk_add_f32 v[38:39], v[38:39], v[38:39] op_sel:[0,1] op_sel_hi:[1,0]
	v_add_f32_e32 v42, v44, v45
	v_add_f32_e32 v44, v46, v47
	v_mov_b32_e32 v43, v50
	v_mov_b32_e32 v45, v51
	v_mov_b32_e32 v37, v48
	v_mov_b32_e32 v39, v49
	v_pk_add_f32 v[36:37], v[36:37], v[38:39]
	v_pk_add_f32 v[38:39], v[42:43], v[44:45]
	s_nop 0
	v_pk_add_f32 v[36:37], v[36:37], v[38:39]
	s_nop 0
	v_add_f32_e32 v36, v36, v37
	v_fmamk_f32 v36, v36, 0x3a800000, v155
	v_rsq_f32_e32 v36, v36

; __device__ __forceinline__ unsigned cvt_pk_bf16(float lo, float hi) { f32x2 v = {lo, hi}; return __builtin_bit_cast(unsigned, __builtin_convertvector(v, nbf16x2e)); }
;     __device__ __forceinline__ void operator()(const f32x4 (&acc)[2][2][4][2], const Unit& u, int wr, int wc, int fr, int fq) const {
;     ...
;                 const int row = row0 + ai * HALF + m * 16;
;                 float rs;
;                 if (rsc) rs = rsc[row - rbase];
;                 else {
;                     const f32x4* pp = (const f32x4*)(part + (size_t)row * 16);
;                     const f32x4 p0 = pp[0], p1 = pp[1], p2 = pp[2], p3 = pp[3];
;                     const float ssq = ((p0[0] + p0[1]) + (p0[2] + p0[3])) + ((p1[0] + p1[1]) + (p1[2] + p1[3])) + ((p2[0] + p2[1]) + (p2[2] + p2[3])) + ((p3[0] + p3[1]) + (p3[2] + p3[3]));
;                     rs = __builtin_amdgcn_rsqf(ssq * (1.0f / 1024.0f) + 1e-6f);
;                 }
;                 float v[8];
; #pragma unroll
;                 for (int n = 0; n < 2; ++n)
; #pragma unroll
;                     for (int i = 0; i < 4; ++i) { const float g = acc[ai][0][m][n][i] * rs, up = acc[ai][1][m][n][i] * rs; v[4 * n + i] = g * __builtin_amdgcn_rcpf(1.0f + __expf(-g)) * up; }
;                 u32x4 w; w.x = cvt_pk_bf16(v[0], v[1]); w.y = cvt_pk_bf16(v[2], v[3]); w.z = cvt_pk_bf16(v[4], v[5]); w.w = cvt_pk_bf16(v[6], v[7]);
;                 *(u32x4*)(O + (size_t)row * 2816 + u.pn * HALF + wc * 32 + 8 * fq) = w;
.LBB0_771:
	s_waitcnt lgkmcnt(0)
	v_pk_mul_f32 v[30:31], v[30:31], v[36:37] op_sel_hi:[1,0]
	v_pk_mul_f32 v[32:33], v[32:33], v[36:37] op_sel_hi:[1,0]
	v_pk_mul_f32 v[26:27], v[26:27], v[36:37] op_sel_hi:[1,0]
	v_pk_mul_f32 v[28:29], v[28:29], v[36:37] op_sel_hi:[1,0]
	v_pk_mul_f32 v[176:177], v[30:31], v[184:185] op_sel_hi:[1,0]
	v_pk_mul_f32 v[178:179], v[32:33], v[184:185] op_sel_hi:[1,0]
	v_pk_mul_f32 v[180:181], v[26:27], v[184:185] op_sel_hi:[1,0]
	v_pk_mul_f32 v[182:183], v[28:29], v[184:185] op_sel_hi:[1,0]
	v_exp_f32_e32 v176, v176
	v_exp_f32_e32 v177, v177
	v_exp_f32_e32 v178, v178
	v_exp_f32_e32 v179, v179
	v_exp_f32_e32 v180, v180
	v_exp_f32_e32 v181, v181
	v_exp_f32_e32 v182, v182
	v_exp_f32_e32 v183, v183
	v_pk_add_f32 v[176:177], v[176:177], v[186:187] op_sel_hi:[1,0]
	v_pk_add_f32 v[178:179], v[178:179], v[186:187] op_sel_hi:[1,0]
	v_pk_add_f32 v[180:181], v[180:181], v[186:187] op_sel_hi:[1,0]
	v_pk_add_f32 v[182:183], v[182:183], v[186:187] op_sel_hi:[1,0]
	v_rcp_f32_e32 v176, v176
	v_rcp_f32_e32 v177, v177
	v_rcp_f32_e32 v178, v178
	v_rcp_f32_e32 v179, v179
	v_rcp_f32_e32 v180, v180
	v_rcp_f32_e32 v181, v181
	v_rcp_f32_e32 v182, v182
	v_rcp_f32_e32 v183, v183
	v_pk_mul_f32 v[22:23], v[22:23], v[36:37] op_sel_hi:[1,0]
	v_pk_mul_f32 v[24:25], v[24:25], v[36:37] op_sel_hi:[1,0]
	v_pk_mul_f32 v[18:19], v[18:19], v[36:37] op_sel_hi:[1,0]
	v_pk_mul_f32 v[20:21], v[20:21], v[36:37] op_sel_hi:[1,0]
	v_pk_mul_f32 v[30:31], v[30:31], v[176:177]
	v_pk_mul_f32 v[32:33], v[32:33], v[178:179]
	v_pk_mul_f32 v[26:27], v[26:27], v[180:181]
	v_pk_mul_f32 v[28:29], v[28:29], v[182:183]
	v_pk_mul_f32 v[22:23], v[22:23], v[30:31]
	v_pk_mul_f32 v[24:25], v[24:25], v[32:33]
	v_pk_mul_f32 v[26:27], v[18:19], v[26:27]
	v_pk_mul_f32 v[28:29], v[20:21], v[28:29]
	v_cvt_pk_bf16_f32 v18, v22, v23
	v_cvt_pk_bf16_f32 v19, v24, v25
	v_cvt_pk_bf16_f32 v20, v26, v27
	v_cvt_pk_bf16_f32 v21, v28, v29
	s_and_b64 vcc, exec, s[36:37]
	v_lshl_add_u64 v[236:237], v[236:237], 0, s[100:101]
	global_store_dwordx4 v[236:237], v[18:21], off
	s_mov_b64 s[26:27], -1
	s_nop 0
	v_add_u32_e32 v18, 0xb0, v148
	v_ashrrev_i32_e32 v19, 31, v18
	s_cbranch_vccz .LBB0_773
	v_lshlrev_b64 v[20:21], 6, v[18:19]
	v_lshl_add_u64 v[32:33], s[8:9], 0, v[20:21]
	global_load_dwordx4 v[20:23], v[32:33], off
	global_load_dwordx4 v[24:27], v[32:33], off offset:16
	global_load_dwordx4 v[28:31], v[32:33], off offset:32
	s_nop 0
	global_load_dwordx4 v[32:35], v[32:33], off offset:48
	s_mov_b64 s[26:27], 0
	s_waitcnt vmcnt(0)
	v_mov_b32_e32 v36, v21
	v_mov_b32_e32 v37, v22
	v_mov_b32_e32 v21, v23
	v_mov_b32_e32 v22, v25
	v_mov_b32_e32 v23, v26
	v_mov_b32_e32 v25, v27
	v_pk_add_f32 v[20:21], v[36:37], v[20:21]
	v_pk_add_f32 v[22:23], v[22:23], v[24:25]
	v_pk_add_f32 v[20:21], v[20:21], v[20:21] op_sel:[0,1] op_sel_hi:[1,0]
	v_pk_add_f32 v[22:23], v[22:23], v[22:23] op_sel:[0,1] op_sel_hi:[1,0]
	v_add_f32_e32 v26, v28, v29
	v_add_f32_e32 v28, v30, v31
	v_mov_b32_e32 v27, v34
	v_mov_b32_e32 v29, v35
	v_mov_b32_e32 v21, v32
	v_mov_b32_e32 v23, v33
	v_pk_add_f32 v[20:21], v[20:21], v[22:23]
	v_pk_add_f32 v[22:23], v[26:27], v[28:29]
	s_nop 0
	v_pk_add_f32 v[20:21], v[20:21], v[22:23]
	s_nop 0
	v_add_f32_e32 v20, v20, v21
	v_fmamk_f32 v20, v20, 0x3a800000, v155
	v_rsq_f32_e32 v20, v20

; __device__ __forceinline__ unsigned cvt_pk_bf16(float lo, float hi) { f32x2 v = {lo, hi}; return __builtin_bit_cast(unsigned, __builtin_convertvector(v, nbf16x2e)); }
;     __device__ __forceinline__ void operator()(const f32x4 (&acc)[2][2][4][2], const Unit& u, int wr, int wc, int fr, int fq) const {
;     ...
;                 const int row = row0 + ai * HALF + m * 16;
;                 float rs;
;                 if (rsc) rs = rsc[row - rbase];
;                 else {
;                     const f32x4* pp = (const f32x4*)(part + (size_t)row * 16);
;                     const f32x4 p0 = pp[0], p1 = pp[1], p2 = pp[2], p3 = pp[3];
;                     const float ssq = ((p0[0] + p0[1]) + (p0[2] + p0[3])) + ((p1[0] + p1[1]) + (p1[2] + p1[3])) + ((p2[0] + p2[1]) + (p2[2] + p2[3])) + ((p3[0] + p3[1]) + (p3[2] + p3[3]));
;                     rs = __builtin_amdgcn_rsqf(ssq * (1.0f / 1024.0f) + 1e-6f);
;                 }
;                 float v[8];
; #pragma unroll
;                 for (int n = 0; n < 2; ++n)
; #pragma unroll
;                     for (int i = 0; i < 4; ++i) { const float g = acc[ai][0][m][n][i] * rs, up = acc[ai][1][m][n][i] * rs; v[4 * n + i] = g * __builtin_amdgcn_rcpf(1.0f + __expf(-g)) * up; }
;                 u32x4 w; w.x = cvt_pk_bf16(v[0], v[1]); w.y = cvt_pk_bf16(v[2], v[3]); w.z = cvt_pk_bf16(v[4], v[5]); w.w = cvt_pk_bf16(v[6], v[7]);
;                 *(u32x4*)(O + (size_t)row * 2816 + u.pn * HALF + wc * 32 + 8 * fq) = w;
.LBB0_775:
	s_waitcnt lgkmcnt(0)
	v_pk_mul_f32 v[14:15], v[14:15], v[20:21] op_sel_hi:[1,0]
	v_pk_mul_f32 v[16:17], v[16:17], v[20:21] op_sel_hi:[1,0]
	v_pk_mul_f32 v[10:11], v[10:11], v[20:21] op_sel_hi:[1,0]
	v_pk_mul_f32 v[12:13], v[12:13], v[20:21] op_sel_hi:[1,0]
	v_pk_mul_f32 v[176:177], v[14:15], v[184:185] op_sel_hi:[1,0]
	v_pk_mul_f32 v[178:179], v[16:17], v[184:185] op_sel_hi:[1,0]
	v_pk_mul_f32 v[180:181], v[10:11], v[184:185] op_sel_hi:[1,0]
	v_pk_mul_f32 v[182:183], v[12:13], v[184:185] op_sel_hi:[1,0]
	v_exp_f32_e32 v176, v176
	v_exp_f32_e32 v177, v177
	v_exp_f32_e32 v178, v178
	v_exp_f32_e32 v179, v179
	v_exp_f32_e32 v180, v180
	v_exp_f32_e32 v181, v181
	v_exp_f32_e32 v182, v182
	v_exp_f32_e32 v183, v183
	v_pk_add_f32 v[176:177], v[176:177], v[186:187] op_sel_hi:[1,0]
	v_pk_add_f32 v[178:179], v[178:179], v[186:187] op_sel_hi:[1,0]
	v_pk_add_f32 v[180:181], v[180:181], v[186:187] op_sel_hi:[1,0]
	v_pk_add_f32 v[182:183], v[182:183], v[186:187] op_sel_hi:[1,0]
	v_rcp_f32_e32 v176, v176
	v_rcp_f32_e32 v177, v177
	v_rcp_f32_e32 v178, v178
	v_rcp_f32_e32 v179, v179
	v_rcp_f32_e32 v180, v180
	v_rcp_f32_e32 v181, v181
	v_rcp_f32_e32 v182, v182
	v_rcp_f32_e32 v183, v183
	v_pk_mul_f32 v[6:7], v[6:7], v[20:21] op_sel_hi:[1,0]
	v_pk_mul_f32 v[8:9], v[8:9], v[20:21] op_sel_hi:[1,0]
	v_pk_mul_f32 v[2:3], v[2:3], v[20:21] op_sel_hi:[1,0]
	v_pk_mul_f32 v[4:5], v[4:5], v[20:21] op_sel_hi:[1,0]
	v_pk_mul_f32 v[14:15], v[14:15], v[176:177]
	v_pk_mul_f32 v[16:17], v[16:17], v[178:179]
	v_pk_mul_f32 v[10:11], v[10:11], v[180:181]
	v_pk_mul_f32 v[12:13], v[12:13], v[182:183]
	v_pk_mul_f32 v[6:7], v[6:7], v[14:15]
	v_pk_mul_f32 v[8:9], v[8:9], v[16:17]
	v_pk_mul_f32 v[10:11], v[2:3], v[10:11]
	v_pk_mul_f32 v[12:13], v[4:5], v[12:13]
	v_cvt_pk_bf16_f32 v2, v6, v7
	v_cvt_pk_bf16_f32 v3, v8, v9
	v_cvt_pk_bf16_f32 v4, v10, v11
	v_cvt_pk_bf16_f32 v5, v12, v13
	s_andn2_b64 vcc, exec, s[0:1]
	s_mov_b64 s[0:1], -1
	v_lshl_add_u64 v[236:237], v[236:237], 0, s[100:101]
	global_store_dwordx4 v[236:237], v[2:5], off
	s_cbranch_vccnz .LBB0_736
	s_andn2_b64 vcc, exec, s[10:11]
	s_cbranch_vccnz .LBB0_735
	s_barrier
	s_branch .LBB0_735
